# FoX main-loop K Q^T: K/Q fragment LDS reads issued 3-5 ahead through rotating register quads, counted lgkmcnt
# baseline (speedup 1.0000x reference)
;     if constexpr (BIAS) {
; #pragma unroll
;         for (int g = 0; g < 4; ++g) { const f32x4 a = *(const f32x4*)(cbt + 8 * g), b = *(const f32x4*)(cbt + 32 + 8 * g);
; #pragma unroll
;             for (int e = 0; e < 4; ++e) { p0[4 * g + e] = a[e]; p1[4 * g + e] = b[e]; } }
;     } else { p0 = f32x16{}; p1 = f32x16{}; }
;     const char* kb[4];
; #pragma unroll
;     for (int dd = 0; dd < 4; ++dd) kb[dd] = K_lds + KB * SHM_K + KSWZ(r32, (dd * 16 + hi * 8) * 2);
; #pragma unroll
;     for (int d0 = 0; d0 < 8; ++d0) { const char* a = kb[d0 & 3] + (d0 >> 2) * 128;
;         bf16x8 b0 = *reinterpret_cast<const bf16x8*>(a);
;         bf16x8 b1 = *reinterpret_cast<const bf16x8*>(a + 32 * 256);
;         bf16x8 q; if (d0 < 8 - QL) q = qr[d0]; else q = *reinterpret_cast<const bf16x8*>(qlds + (d0 - (8 - QL)) * 1024);
;         p0 = __builtin_amdgcn_mfma_f32_32x32x16_bf16(b0, q, p0, 0, 0, 0);
;         p1 = __builtin_amdgcn_mfma_f32_32x32x16_bf16(b1, q, p1, 0, 0, 0); }
; }
.LBB0_1176:
	s_add_i32 s73, s72, 1
	s_cmp_ge_i32 s73, s30
	s_cselect_b64 s[10:11], -1, 0
	s_cmp_le_i32 s73, s31
	s_cselect_b64 s[12:13], -1, 0
	s_and_b64 s[12:13], s[10:11], s[12:13]
	s_waitcnt vmcnt(3)
	v_cndmask_b32_e64 v160, 0, 1, s[12:13]
	v_cmp_ne_u32_e64 s[10:11], 1, v160
	s_andn2_b64 vcc, exec, s[12:13]
	s_cbranch_vccnz .LBB0_1178
	ds_read_b128 v[80:83], v202
	ds_read_b128 v[84:87], v202 offset:32
	ds_read_b128 v[88:91], v202 offset:64
	ds_read_b128 v[92:95], v202 offset:96
	ds_read_b128 v[64:67], v202 offset:128
	ds_read_b128 v[68:71], v202 offset:160
	ds_read_b128 v[72:75], v202 offset:192
	ds_read_b128 v[76:79], v202 offset:224
	ds_read_b128 v[224:227], v204 offset:49152
	ds_read_b128 v[228:231], v204 offset:57344
	ds_read_b128 v[232:235], v205 offset:49152
	ds_read_b128 v[236:239], v205 offset:57344
	s_waitcnt lgkmcnt(3)
	v_mfma_f32_32x32x16_bf16 v[80:95], v[224:227], v[140:143], v[80:95]
	ds_read_b128 v[224:227], v206 offset:49152
	s_waitcnt lgkmcnt(3)
	v_mfma_f32_32x32x16_bf16 v[64:79], v[228:231], v[140:143], v[64:79]
	ds_read_b128 v[228:231], v206 offset:57344
	s_waitcnt lgkmcnt(3)
	v_mfma_f32_32x32x16_bf16 v[80:95], v[232:235], v[132:135], v[80:95]
	ds_read_b128 v[232:235], v207 offset:49152
	s_waitcnt lgkmcnt(3)
	v_mfma_f32_32x32x16_bf16 v[64:79], v[236:239], v[132:135], v[64:79]
	ds_read_b128 v[236:239], v207 offset:57344
	s_waitcnt lgkmcnt(3)
	v_mfma_f32_32x32x16_bf16 v[80:95], v[224:227], v[136:139], v[80:95]
	ds_read_b128 v[240:243], v195
	ds_read_b128 v[224:227], v204 offset:49280
	s_waitcnt lgkmcnt(4)
	v_mfma_f32_32x32x16_bf16 v[64:79], v[228:231], v[136:139], v[64:79]
	ds_read_b128 v[228:231], v204 offset:57472
	s_waitcnt lgkmcnt(4)
	v_mfma_f32_32x32x16_bf16 v[80:95], v[232:235], v[128:131], v[80:95]
	ds_read_b128 v[244:247], v195 offset:1024
	ds_read_b128 v[232:235], v205 offset:49280
	s_waitcnt lgkmcnt(5)
	v_mfma_f32_32x32x16_bf16 v[64:79], v[236:239], v[128:131], v[64:79]
	ds_read_b128 v[236:239], v205 offset:57472
	s_waitcnt vmcnt(2)
	s_waitcnt lgkmcnt(4)
	v_mfma_f32_32x32x16_bf16 v[80:95], v[224:227], v[240:243], v[80:95]
	ds_read_b128 v[224:227], v206 offset:49280
	s_waitcnt lgkmcnt(4)
	v_mfma_f32_32x32x16_bf16 v[64:79], v[228:231], v[240:243], v[64:79]
	ds_read_b128 v[240:243], v195 offset:2048
	ds_read_b128 v[228:231], v206 offset:57472
	s_waitcnt lgkmcnt(4)
	v_mfma_f32_32x32x16_bf16 v[80:95], v[232:235], v[244:247], v[80:95]
	ds_read_b128 v[232:235], v207 offset:49280
	s_waitcnt lgkmcnt(4)
	v_mfma_f32_32x32x16_bf16 v[64:79], v[236:239], v[244:247], v[64:79]
	ds_read_b128 v[244:247], v195 offset:3072
	ds_read_b128 v[236:239], v207 offset:57472
	s_waitcnt lgkmcnt(4)
	v_mfma_f32_32x32x16_bf16 v[80:95], v[224:227], v[240:243], v[80:95]
	s_waitcnt lgkmcnt(3)
	v_mfma_f32_32x32x16_bf16 v[64:79], v[228:231], v[240:243], v[64:79]
	s_waitcnt lgkmcnt(1)
	v_mfma_f32_32x32x16_bf16 v[80:95], v[232:235], v[244:247], v[80:95]
	s_waitcnt lgkmcnt(0)
	v_mfma_f32_32x32x16_bf16 v[64:79], v[236:239], v[244:247], v[64:79]

;     if constexpr (BIAS) {
; #pragma unroll
;         for (int g = 0; g < 4; ++g) { const f32x4 a = *(const f32x4*)(cbt + 8 * g), b = *(const f32x4*)(cbt + 32 + 8 * g);
; #pragma unroll
;             for (int e = 0; e < 4; ++e) { p0[4 * g + e] = a[e]; p1[4 * g + e] = b[e]; } }
;     } else { p0 = f32x16{}; p1 = f32x16{}; }
;     const char* kb[4];
; #pragma unroll
;     for (int dd = 0; dd < 4; ++dd) kb[dd] = K_lds + KB * SHM_K + KSWZ(r32, (dd * 16 + hi * 8) * 2);
; #pragma unroll
;     for (int d0 = 0; d0 < 8; ++d0) { const char* a = kb[d0 & 3] + (d0 >> 2) * 128;
;         bf16x8 b0 = *reinterpret_cast<const bf16x8*>(a);
;         bf16x8 b1 = *reinterpret_cast<const bf16x8*>(a + 32 * 256);
;         bf16x8 q; if (d0 < 8 - QL) q = qr[d0]; else q = *reinterpret_cast<const bf16x8*>(qlds + (d0 - (8 - QL)) * 1024);
;         p0 = __builtin_amdgcn_mfma_f32_32x32x16_bf16(b0, q, p0, 0, 0, 0);
;         p1 = __builtin_amdgcn_mfma_f32_32x32x16_bf16(b1, q, p1, 0, 0, 0); }
; }
.LBB0_1191:
	s_add_i32 s35, s72, 2
	s_waitcnt lgkmcnt(0)
	s_barrier
	s_cmp_ge_i32 s35, s30
	s_cselect_b64 s[12:13], -1, 0
	s_cmp_lt_i32 s73, s31
	s_cselect_b64 s[38:39], -1, 0
	s_and_b64 s[38:39], s[12:13], s[38:39]
	v_cndmask_b32_e64 v208, 0, 1, s[38:39]
	v_cmp_ne_u32_e64 s[12:13], 1, v208
	s_andn2_b64 vcc, exec, s[38:39]
	s_cbranch_vccnz .LBB0_1193
	ds_read_b128 v[112:115], v202 offset:256
	ds_read_b128 v[116:119], v202 offset:288
	ds_read_b128 v[120:123], v202 offset:320
	ds_read_b128 v[124:127], v202 offset:352
	ds_read_b128 v[96:99], v202 offset:384
	ds_read_b128 v[100:103], v202 offset:416
	ds_read_b128 v[104:107], v202 offset:448
	ds_read_b128 v[108:111], v202 offset:480
	ds_read_b128 v[224:227], v204 offset:32768
	ds_read_b128 v[228:231], v204 offset:40960
	ds_read_b128 v[232:235], v205 offset:32768
	ds_read_b128 v[236:239], v205 offset:40960
	s_waitcnt lgkmcnt(3)
	v_mfma_f32_32x32x16_bf16 v[112:127], v[224:227], v[140:143], v[112:127]
	ds_read_b128 v[224:227], v206 offset:32768
	s_waitcnt lgkmcnt(3)
	v_mfma_f32_32x32x16_bf16 v[96:111], v[228:231], v[140:143], v[96:111]
	ds_read_b128 v[228:231], v206 offset:40960
	s_waitcnt lgkmcnt(3)
	v_mfma_f32_32x32x16_bf16 v[112:127], v[232:235], v[132:135], v[112:127]
	ds_read_b128 v[232:235], v207 offset:32768
	s_waitcnt lgkmcnt(3)
	v_mfma_f32_32x32x16_bf16 v[96:111], v[236:239], v[132:135], v[96:111]
	ds_read_b128 v[236:239], v207 offset:40960
	s_waitcnt lgkmcnt(3)
	v_mfma_f32_32x32x16_bf16 v[112:127], v[224:227], v[136:139], v[112:127]
	ds_read_b128 v[240:243], v195
	ds_read_b128 v[224:227], v204 offset:32896
	s_waitcnt lgkmcnt(4)
	v_mfma_f32_32x32x16_bf16 v[96:111], v[228:231], v[136:139], v[96:111]
	ds_read_b128 v[228:231], v204 offset:41088
	s_waitcnt lgkmcnt(4)
	v_mfma_f32_32x32x16_bf16 v[112:127], v[232:235], v[128:131], v[112:127]
	ds_read_b128 v[244:247], v195 offset:1024
	ds_read_b128 v[232:235], v205 offset:32896
	s_waitcnt lgkmcnt(5)
	v_mfma_f32_32x32x16_bf16 v[96:111], v[236:239], v[128:131], v[96:111]
	ds_read_b128 v[236:239], v205 offset:41088
	s_waitcnt lgkmcnt(4)
	v_mfma_f32_32x32x16_bf16 v[112:127], v[224:227], v[240:243], v[112:127]
	ds_read_b128 v[224:227], v206 offset:32896
	s_waitcnt lgkmcnt(4)
	v_mfma_f32_32x32x16_bf16 v[96:111], v[228:231], v[240:243], v[96:111]
	ds_read_b128 v[240:243], v195 offset:2048
	ds_read_b128 v[228:231], v206 offset:41088
	s_waitcnt lgkmcnt(4)
	v_mfma_f32_32x32x16_bf16 v[112:127], v[232:235], v[244:247], v[112:127]
	ds_read_b128 v[232:235], v207 offset:32896
	s_waitcnt lgkmcnt(4)
	v_mfma_f32_32x32x16_bf16 v[96:111], v[236:239], v[244:247], v[96:111]
	ds_read_b128 v[244:247], v195 offset:3072
	ds_read_b128 v[236:239], v207 offset:41088
	s_waitcnt lgkmcnt(4)
	v_mfma_f32_32x32x16_bf16 v[112:127], v[224:227], v[240:243], v[112:127]
	s_waitcnt lgkmcnt(3)
	v_mfma_f32_32x32x16_bf16 v[96:111], v[228:231], v[240:243], v[96:111]
	s_waitcnt lgkmcnt(1)
	v_mfma_f32_32x32x16_bf16 v[112:127], v[232:235], v[244:247], v[112:127]
	s_waitcnt lgkmcnt(0)
	v_mfma_f32_32x32x16_bf16 v[96:111], v[236:239], v[244:247], v[96:111]
